# delta scan: next chunk's raw rows staged before the step-end barrier, chunk-top barrier dropped for chunks > 0
# speedup vs baseline: 1.0027x; 1.0027x over previous
; __device__ __forceinline__ float bflo(unsigned u) { return __uint_as_float(u << 16); }
; __device__ __forceinline__ float bfhi(unsigned u) { return __uint_as_float(u & 0xffff0000u); }
; template <int MIX>
; __device__ __forceinline__ void scan_part(const Params& p, const int layer, const int smp, const int b0, const int bstep, const int bend, const int h, const int part, char* lds, const int tid) {
;     ...
;   for (int t0 = 0; t0 < T; t0 += 32) {
;     const int ntok = min(32, T - t0);
;     ntok_last = ntok;
;     const bool valid = tt < ntok;
;     float* dst = qkdv + tt * 256;
;     if (MIX != 0 && valid) {
;       if (VN == 4) *(f32x4*)(dst + 192 + sub * 4) = (f32x4){bflo(R2.x), bfhi(R2.x), bflo(R2.y), bfhi(R2.y)};
;       else *(float2*)(dst + 192 + sub * 2) = make_float2(bflo(R2.x), bfhi(R2.x));
;     }
;     if (MIX == 0) {
;       if (valid) {
;         *(uint4*)(rawb + (3 + tt) * RS + 0 + sub * 8) = R0;
;         *(uint4*)(rawb + (3 + tt) * RS + 64 + sub * 8) = R1;
;         if (VN == 4) *(uint2*)(rawb + (3 + tt) * RS + 128 + sub * 4) = R2;
;         else *(unsigned*)(rawb + (3 + tt) * RS + 128 + sub * 2) = R2.x;
;       }
;       __syncthreads();
;       if (valid) {
.LBB0_421:
	s_sub_i32 s26, 0x810, s23
	s_min_u32 s26, s26, 32
	s_waitcnt vmcnt(2)
	s_cmp_eq_u32 s23, 0
	s_cbranch_scc1 .Ldcarry_skip
	v_cmp_gt_i32_e64 s[42:43], s26, v131
	s_branch .Ld_top_done

; __device__ __forceinline__ float bflo(unsigned u) { return __uint_as_float(u << 16); }
; __device__ __forceinline__ float bfhi(unsigned u) { return __uint_as_float(u & 0xffff0000u); }
; template <int N, int RS>
; __device__ __forceinline__ void convN(const bf16_t* rawb, const float (&w)[4][N], int tt, int off, float (&x)[N]) {
; #pragma unroll
;   for (int i = 0; i < N; ++i) x[i] = 0.f;
; #pragma unroll
;   for (int j = 0; j < 4; ++j) {
;     float xv[N];
;     if (N == 8) { const uint4 rv = *(const uint4*)(rawb + (tt + j) * RS + off); unpack8(rv, xv); }
;     else if (N == 4) { const uint2 rv = *(const uint2*)(rawb + (tt + j) * RS + off); xv[0] = bflo(rv.x); xv[1] = bfhi(rv.x); xv[2 % N] = bflo(rv.y); xv[3 % N] = bfhi(rv.y); }
;     else { const unsigned rv = *(const unsigned*)(rawb + (tt + j) * RS + off); xv[0] = bflo(rv); xv[1] = bfhi(rv); }
; #pragma unroll
;     for (int i = 0; i < N; ++i) x[i] += w[j][i] * xv[i];
;   }
; template <int MIX>
; __device__ __forceinline__ void scan_part(const Params& p, const int layer, const int smp, const int b0, const int bstep, const int bend, const int h, const int part, char* lds, const int tid) {
;     ...
;       if (valid) {
;         float xq[8], xk[8], xv[VN];
;         { float cwv[4][VN];
; #pragma unroll
;           for (int j = 0; j < 4; ++j)
; #pragma unroll
;             for (int i = 0; i < VN; ++i) cwv[j][i] = cwl[j * RS + 128 + sub * VN + i];
;           convN<VN, RS>(rawb, cwv, tt, 128 + sub * VN, xv); }
;         convN<8, RS>(rawb, cwq, tt, sub * 8, xq);
;         convN<8, RS>(rawb, cwk, tt, 64 + sub * 8, xk);
.Ld_top_done:
	s_and_saveexec_b64 s[50:51], s[42:43]
	s_cbranch_execz .LBB0_426
	v_add_u32_e32 v2, v140, v138
	v_add_u32_e32 v0, 0x9200, v2
	v_add_u32_e32 v76, 0xbc00, v137
	ds_read2_b32 v[0:1], v0 offset0:64 offset1:136
	ds_read2_b64 v[76:79], v76 offset0:120 offset1:192
	v_add_u32_e32 v80, 0xc000, v137
	v_add_u32_e32 v2, 0x9400, v2
	ds_read2_b64 v[80:83], v80 offset0:136 offset1:208
	s_waitcnt lgkmcnt(2)
	v_lshlrev_b32_e32 v85, 16, v1
	v_lshlrev_b32_e32 v84, 16, v0
	s_waitcnt lgkmcnt(1)
	v_mov_b32_e32 v86, v76
	v_mov_b32_e32 v87, v78
	v_pk_mul_f32 v[84:85], v[86:87], v[84:85]
	v_and_b32_e32 v1, 0xffff0000, v1
	v_add_f32_e32 v76, 0, v84
	v_add_f32_e32 v86, v76, v85
	ds_read2_b32 v[84:85], v2 offset0:80 offset1:152
	v_and_b32_e32 v0, 0xffff0000, v0
	v_mov_b32_e32 v78, v77
	v_pk_mul_f32 v[0:1], v[78:79], v[0:1]
	s_waitcnt lgkmcnt(1)
	v_mov_b32_e32 v76, v80
	v_add_f32_e32 v0, 0, v0
	v_add_f32_e32 v2, v0, v1
	s_waitcnt lgkmcnt(0)
	v_lshlrev_b32_e32 v1, 16, v85
	v_lshlrev_b32_e32 v0, 16, v84
	v_mov_b32_e32 v77, v82
	v_pk_mul_f32 v[0:1], v[76:77], v[0:1]
	v_and_b32_e32 v77, 0xffff0000, v85
	v_and_b32_e32 v76, 0xffff0000, v84
	v_mov_b32_e32 v82, v81
	v_add_f32_e32 v0, v86, v0
	v_pk_mul_f32 v[76:77], v[82:83], v[76:77]
	v_add_f32_e32 v0, v0, v1
	v_add_f32_e32 v1, v2, v76
	v_add_f32_e32 v1, v1, v77
	ds_read_b128 v[78:81], v151 offset:37376
	ds_read_b128 v[82:85], v151 offset:37504
	ds_read_b128 v[86:89], v151 offset:37664
	ds_read_b128 v[90:93], v151 offset:37952
	v_mul_f32_e32 v2, 0xbfb8aa3b, v0
	ds_read_b128 v[174:177], v151 offset:38240
	v_exp_f32_e32 v2, v2
	v_mul_f32_e32 v76, 0xbfb8aa3b, v1
	v_exp_f32_e32 v77, v76
	s_waitcnt lgkmcnt(4)
	v_lshlrev_b32_e32 v154, 16, v80
	v_and_b32_e32 v155, 0xffff0000, v80
	v_lshlrev_b32_e32 v94, 16, v78
	v_and_b32_e32 v95, 0xffff0000, v78
	v_lshlrev_b32_e32 v106, 16, v79
	v_and_b32_e32 v107, 0xffff0000, v79
	v_lshlrev_b32_e32 v178, 16, v81
	v_and_b32_e32 v179, 0xffff0000, v81
	ds_read_b128 v[78:81], v151 offset:37792
	s_waitcnt lgkmcnt(3)
	v_lshlrev_b32_e32 v180, 16, v86
	v_and_b32_e32 v181, 0xffff0000, v86
	v_lshlrev_b32_e32 v182, 16, v87
	v_and_b32_e32 v183, 0xffff0000, v87
	v_lshlrev_b32_e32 v184, 16, v88
	v_and_b32_e32 v185, 0xffff0000, v88
	v_lshlrev_b32_e32 v186, 16, v89
	v_and_b32_e32 v187, 0xffff0000, v89
	ds_read_b128 v[86:89], v151 offset:38080
	s_waitcnt lgkmcnt(3)
	v_lshlrev_b32_e32 v188, 16, v90
	v_and_b32_e32 v189, 0xffff0000, v90
	v_lshlrev_b32_e32 v190, 16, v91
	v_and_b32_e32 v191, 0xffff0000, v91
	v_lshlrev_b32_e32 v192, 16, v92
	v_and_b32_e32 v193, 0xffff0000, v92
	v_lshlrev_b32_e32 v194, 16, v93
	v_and_b32_e32 v195, 0xffff0000, v93
	ds_read_b128 v[90:93], v151 offset:38368
	s_waitcnt vmcnt(2)
	v_pk_fma_f32 v[154:155], v[4:5], v[154:155], 0 op_sel_hi:[1,1,0]
	v_add_f32_e32 v2, 1.0, v2
	s_waitcnt vmcnt(2)
	v_pk_fma_f32 v[154:155], v[12:13], v[184:185], v[154:155]
	s_waitcnt lgkmcnt(3)
	v_lshlrev_b32_e32 v198, 16, v176
	v_and_b32_e32 v199, 0xffff0000, v176
	s_waitcnt vmcnt(2)
	v_pk_fma_f32 v[154:155], v[20:21], v[192:193], v[154:155]
	v_rcp_f32_e32 v76, v2
	v_add_f32_e32 v2, 1.0, v77
	s_waitcnt vmcnt(2)
	v_pk_fma_f32 v[154:155], v[28:29], v[198:199], v[154:155]
	v_rcp_f32_e32 v77, v2
	v_mul_f32_e32 v2, 0xbfb8aa3b, v154
	v_lshlrev_b32_e32 v202, 16, v84
	v_and_b32_e32 v203, 0xffff0000, v84
	s_waitcnt lgkmcnt(0)
	v_lshlrev_b32_e32 v214, 16, v92
	v_and_b32_e32 v215, 0xffff0000, v92
	v_exp_f32_e32 v2, v2
	v_mul_f32_e32 v92, 0xbfb8aa3b, v155
	v_lshlrev_b32_e32 v206, 16, v80
	v_and_b32_e32 v207, 0xffff0000, v80
	v_exp_f32_e32 v158, v92
	s_waitcnt vmcnt(2)
	v_pk_fma_f32 v[192:193], v[36:37], v[202:203], 0 op_sel_hi:[1,1,0]
	v_lshlrev_b32_e32 v210, 16, v88
	v_and_b32_e32 v211, 0xffff0000, v88
	s_waitcnt vmcnt(2)
	v_pk_fma_f32 v[192:193], v[44:45], v[206:207], v[192:193]
	v_add_f32_e32 v2, 1.0, v2
	s_waitcnt vmcnt(2)
	v_pk_fma_f32 v[192:193], v[52:53], v[210:211], v[192:193]
	v_rcp_f32_e32 v184, v2
	s_waitcnt vmcnt(2)
	v_pk_fma_f32 v[192:193], v[60:61], v[214:215], v[192:193]
	v_add_f32_e32 v2, 1.0, v158
	v_mul_f32_e32 v158, 0xbfb8aa3b, v192
	v_exp_f32_e32 v158, v158
	v_mul_f32_e32 v159, 0xbfb8aa3b, v193
	v_exp_f32_e32 v159, v159
	v_pk_fma_f32 v[178:179], v[6:7], v[178:179], 0 op_sel_hi:[1,1,0]
	v_lshlrev_b32_e32 v176, 16, v177
	v_pk_fma_f32 v[178:179], v[14:15], v[186:187], v[178:179]
	v_and_b32_e32 v177, 0xffff0000, v177
	v_rcp_f32_e32 v185, v2
	v_add_f32_e32 v2, 1.0, v158
	v_pk_fma_f32 v[178:179], v[22:23], v[194:195], v[178:179]
	v_rcp_f32_e32 v198, v2
	v_add_f32_e32 v2, 1.0, v159
	v_pk_fma_f32 v[176:177], v[30:31], v[176:177], v[178:179]
	v_rcp_f32_e32 v199, v2
	v_mul_f32_e32 v2, 0xbfb8aa3b, v176
	v_exp_f32_e32 v2, v2
	v_mul_f32_e32 v158, 0xbfb8aa3b, v177
	v_exp_f32_e32 v158, v158
	v_pk_fma_f32 v[94:95], v[8:9], v[94:95], 0 op_sel_hi:[1,1,0]
	v_lshlrev_b32_e32 v196, 16, v174
	v_pk_fma_f32 v[94:95], v[16:17], v[180:181], v[94:95]
	v_and_b32_e32 v197, 0xffff0000, v174
	v_add_f32_e32 v2, 1.0, v2
	v_pk_fma_f32 v[94:95], v[24:25], v[188:189], v[94:95]
	v_rcp_f32_e32 v186, v2
	v_add_f32_e32 v2, 1.0, v158
	v_pk_fma_f32 v[94:95], v[32:33], v[196:197], v[94:95]
	v_rcp_f32_e32 v187, v2
	v_mul_f32_e32 v2, 0xbfb8aa3b, v94
	v_exp_f32_e32 v2, v2
	v_mul_f32_e32 v158, 0xbfb8aa3b, v95
	v_exp_f32_e32 v158, v158
	v_pk_fma_f32 v[106:107], v[10:11], v[106:107], 0 op_sel_hi:[1,1,0]
	v_lshlrev_b32_e32 v174, 16, v175
	v_pk_fma_f32 v[106:107], v[18:19], v[182:183], v[106:107]
	v_and_b32_e32 v175, 0xffff0000, v175
	v_pk_fma_f32 v[106:107], v[26:27], v[190:191], v[106:107]
	v_add_f32_e32 v2, 1.0, v2
	v_pk_fma_f32 v[106:107], v[34:35], v[174:175], v[106:107]
	v_rcp_f32_e32 v180, v2
	v_add_f32_e32 v2, 1.0, v158
; __device__ __forceinline__ float bflo(unsigned u) { return __uint_as_float(u << 16); }
; __device__ __forceinline__ float sigmoidf_(float x) { return __builtin_amdgcn_rcpf(1.0f + __expf(-x)); }
; __device__ __forceinline__ float softplusf_(float x) { return fmaxf(x, 0.f) + __logf(1.0f + __expf(-fabsf(x))); }
; __device__ __forceinline__ float red8d(float x) { x += dpp_x1(x); x += dpp_x2(x); x += dpp_hm(x); return x; }
; template <int MIX>
; __device__ __forceinline__ void scan_part(const Params& p, const int layer, const int smp, const int b0, const int bstep, const int bend, const int h, const int part, char* lds, const int tid) {
;     ...
;         convN<8, RS>(rawb, cwq, tt, sub * 8, xq);
;         convN<8, RS>(rawb, cwk, tt, 64 + sub * 8, xk);
; #pragma unroll
;         for (int i = 0; i < VN; ++i) dst[192 + sub * VN + i] = xv[i];
;         float ssq = 0.f, ssk = 0.f;
; #pragma unroll
;         for (int i = 0; i < 8; ++i) { ssq += xq[i] * xq[i]; ssk += xk[i] * xk[i]; }
;         ssq = red8d(ssq); ssk = red8d(ssk);
;         const float rq = rsqrtf(ssq + 1e-6f) * 0.125f, rk = rsqrtf(ssk + 1e-6f);
;         float qk = 0.f;
; #pragma unroll
;         for (int i = 0; i < 8; ++i) { xq[i] *= rq; xk[i] *= rk; qk += xq[i] * xk[i]; }
;         qk = red8d(qk);
;         *(f32x4*)(dst + sub * 8) = (f32x4){xq[0], xq[1], xq[2], xq[3]}; *(f32x4*)(dst + sub * 8 + 4) = (f32x4){xq[4], xq[5], xq[6], xq[7]};
;         *(f32x4*)(dst + 64 + sub * 8) = (f32x4){xk[0], xk[1], xk[2], xk[3]}; *(f32x4*)(dst + 64 + sub * 8 + 4) = (f32x4){xk[4], xk[5], xk[6], xk[7]};
;         if (sub == 0) {
;           const float be = sigmoidf_(bflo(ex0)), al = bflo(ex1);
;           const float a = __expf(-Aexp * softplusf_(al + dtb));
;           *(f32x4*)(scal + tt * 4) = (f32x4){a, be, qk, 0.f};
	v_mul_f32_e32 v158, 0xbfb8aa3b, v106
	v_exp_f32_e32 v158, v158
	v_mul_f32_e32 v159, 0xbfb8aa3b, v107
	v_lshlrev_b32_e32 v84, 16, v85
	v_and_b32_e32 v85, 0xffff0000, v85
	v_exp_f32_e32 v159, v159
	v_lshlrev_b32_e32 v80, 16, v81
	v_and_b32_e32 v81, 0xffff0000, v81
	v_pk_fma_f32 v[84:85], v[38:39], v[84:85], 0 op_sel_hi:[1,1,0]
	v_lshlrev_b32_e32 v88, 16, v89
	v_and_b32_e32 v89, 0xffff0000, v89
	v_pk_fma_f32 v[80:81], v[46:47], v[80:81], v[84:85]
	v_lshlrev_b32_e32 v92, 16, v93
	v_and_b32_e32 v93, 0xffff0000, v93
	v_rcp_f32_e32 v181, v2
	v_add_f32_e32 v2, 1.0, v158
	v_pk_fma_f32 v[80:81], v[54:55], v[88:89], v[80:81]
	v_rcp_f32_e32 v174, v2
	v_add_f32_e32 v2, 1.0, v159
	v_pk_fma_f32 v[80:81], v[62:63], v[92:93], v[80:81]
	v_rcp_f32_e32 v175, v2
	v_mul_f32_e32 v2, 0xbfb8aa3b, v80
	v_exp_f32_e32 v2, v2
	v_mul_f32_e32 v84, 0xbfb8aa3b, v81
	v_exp_f32_e32 v89, v84
	v_lshlrev_b32_e32 v200, 16, v82
	v_and_b32_e32 v201, 0xffff0000, v82
	v_lshlrev_b32_e32 v204, 16, v78
	v_and_b32_e32 v205, 0xffff0000, v78
	v_add_f32_e32 v2, 1.0, v2
	v_pk_fma_f32 v[92:93], v[40:41], v[200:201], 0 op_sel_hi:[1,1,0]
	v_lshlrev_b32_e32 v82, 16, v83
	v_and_b32_e32 v83, 0xffff0000, v83
	v_lshlrev_b32_e32 v208, 16, v86
	v_and_b32_e32 v209, 0xffff0000, v86
	v_rcp_f32_e32 v88, v2
	v_add_f32_e32 v2, 1.0, v89
	v_pk_fma_f32 v[92:93], v[48:49], v[204:205], v[92:93]
	v_lshlrev_b32_e32 v78, 16, v79
	v_and_b32_e32 v79, 0xffff0000, v79
	v_lshlrev_b32_e32 v212, 16, v90
	v_and_b32_e32 v213, 0xffff0000, v90
	v_rcp_f32_e32 v89, v2
	v_pk_fma_f32 v[92:93], v[56:57], v[208:209], v[92:93]
	v_pk_fma_f32 v[82:83], v[42:43], v[82:83], 0 op_sel_hi:[1,1,0]
	v_lshlrev_b32_e32 v86, 16, v87
	v_and_b32_e32 v87, 0xffff0000, v87
	s_waitcnt vmcnt(2)
	v_pk_fma_f32 v[92:93], v[64:65], v[212:213], v[92:93]
	v_pk_fma_f32 v[78:79], v[50:51], v[78:79], v[82:83]
	v_lshlrev_b32_e32 v90, 16, v91
	v_and_b32_e32 v91, 0xffff0000, v91
	v_mul_f32_e32 v2, 0xbfb8aa3b, v92
	v_pk_fma_f32 v[78:79], v[58:59], v[86:87], v[78:79]
	v_exp_f32_e32 v2, v2
	v_mul_f32_e32 v158, 0xbfb8aa3b, v93
	v_pk_fma_f32 v[78:79], v[66:67], v[90:91], v[78:79]
	v_pk_mul_f32 v[106:107], v[106:107], v[174:175]
	v_exp_f32_e32 v158, v158
	v_pk_mul_f32 v[174:175], v[80:81], v[88:89]
	v_mul_f32_e32 v81, 0xbfb8aa3b, v78
	v_exp_f32_e32 v82, v81
	v_mul_f32_e32 v81, 0xbfb8aa3b, v79
	v_exp_f32_e32 v83, v81
	v_add_f32_e32 v2, 1.0, v2
	v_rcp_f32_e32 v80, v2
	v_add_f32_e32 v2, 1.0, v158
	v_rcp_f32_e32 v81, v2
	v_add_f32_e32 v2, 1.0, v82
	v_rcp_f32_e32 v82, v2
	v_add_f32_e32 v2, 1.0, v83
	v_rcp_f32_e32 v83, v2
	v_pk_mul_f32 v[94:95], v[94:95], v[180:181]
	v_pk_mul_f32 v[88:89], v[92:93], v[80:81]
	v_pk_mul_f32 v[180:181], v[94:95], v[94:95]
	v_pk_mul_f32 v[80:81], v[88:89], v[88:89]
	v_pk_mul_f32 v[90:91], v[78:79], v[82:83]
	v_pk_mul_f32 v[84:85], v[106:107], v[106:107]
	v_pk_mul_f32 v[78:79], v[90:91], v[90:91]
	v_mov_b32_e32 v82, v80
	v_mov_b32_e32 v83, v180
	v_mov_b32_e32 v180, v81
	v_pk_mul_f32 v[154:155], v[154:155], v[184:185]
	v_pk_mul_f32 v[192:193], v[192:193], v[198:199]
	v_pk_add_f32 v[80:81], v[82:83], v[180:181]
	v_mov_b32_e32 v82, v78
	v_mov_b32_e32 v83, v84
	v_pk_mul_f32 v[184:185], v[154:155], v[154:155]
	v_pk_mul_f32 v[178:179], v[192:193], v[192:193]
	v_pk_add_f32 v[80:81], v[80:81], v[82:83]
	v_mov_b32_e32 v84, v79
	v_pk_mul_f32 v[176:177], v[176:177], v[186:187]
	v_pk_add_f32 v[78:79], v[84:85], v[80:81]
	v_mov_b32_e32 v80, v178
	v_mov_b32_e32 v81, v184
	v_pk_mul_f32 v[182:183], v[176:177], v[176:177]
	v_pk_mul_f32 v[86:87], v[174:175], v[174:175]
	v_pk_add_f32 v[78:79], v[80:81], v[78:79]
	v_mov_b32_e32 v184, v179
	v_pk_add_f32 v[78:79], v[184:185], v[78:79]
	v_mov_b32_e32 v80, v86
	v_mov_b32_e32 v81, v182
	v_pk_add_f32 v[78:79], v[80:81], v[78:79]
	v_mov_b32_e32 v182, v87
	v_pk_add_f32 v[78:79], v[182:183], v[78:79]
	s_mov_b32 s44, 0x358637bd
	v_pk_mul_f32 v[0:1], v[0:1], v[76:77]
	v_mov_b32_dpp v81, v79 quad_perm:[1,0,3,2] row_mask:0xf bank_mask:0xf bound_ctrl:1
	v_mov_b32_dpp v80, v78 quad_perm:[1,0,3,2] row_mask:0xf bank_mask:0xf bound_ctrl:1
	v_pk_add_f32 v[78:79], v[78:79], v[80:81]
	ds_write_b64 v141, v[0:1] offset:768
	s_nop 0
	v_mov_b32_dpp v81, v79 quad_perm:[2,3,0,1] row_mask:0xf bank_mask:0xf bound_ctrl:1
	v_mov_b32_dpp v80, v78 quad_perm:[2,3,0,1] row_mask:0xf bank_mask:0xf bound_ctrl:1
	v_pk_add_f32 v[78:79], v[78:79], v[80:81]
	s_nop 1
	v_mov_b32_dpp v81, v79 row_half_mirror row_mask:0xf bank_mask:0xf bound_ctrl:1
	v_mov_b32_dpp v80, v78 row_half_mirror row_mask:0xf bank_mask:0xf bound_ctrl:1
	v_pk_add_f32 v[78:79], v[78:79], v[80:81]
	s_nop 0
	v_pk_add_f32 v[78:79], v[78:79], s[44:45] op_sel_hi:[1,0]
	s_nop 0
	v_mul_f32_e32 v2, 0x4b800000, v79
	v_cmp_gt_f32_e32 vcc, s92, v79
	s_nop 1
	v_cndmask_b32_e32 v2, v79, v2, vcc
	v_rsq_f32_e32 v2, v2
	s_nop 0
	v_mul_f32_e32 v0, 0x45800000, v2
	v_cndmask_b32_e32 v0, v2, v0, vcc
	v_mul_f32_e32 v0, 0x3e000000, v0
	v_pk_mul_f32 v[76:77], v[94:95], v[0:1] op_sel_hi:[1,0]
	v_mul_f32_e32 v1, 0x4b800000, v78
	v_cmp_gt_f32_e32 vcc, s92, v78
	s_nop 1
	v_cndmask_b32_e32 v1, v78, v1, vcc
	v_rsq_f32_e32 v1, v1
	s_nop 0
	v_pk_mul_f32 v[78:79], v[106:107], v[0:1] op_sel_hi:[1,0]
	v_pk_mul_f32 v[80:81], v[154:155], v[0:1] op_sel_hi:[1,0]
	v_pk_mul_f32 v[82:83], v[176:177], v[0:1] op_sel_hi:[1,0]
	v_mul_f32_e32 v0, 0x45800000, v1
	v_cndmask_b32_e32 v0, v1, v0, vcc
	v_pk_mul_f32 v[84:85], v[88:89], v[0:1] op_sel_hi:[1,0]
	s_nop 0
	v_pk_mul_f32 v[86:87], v[90:91], v[0:1] op_sel_hi:[1,0]
	s_nop 0
	v_pk_mul_f32 v[88:89], v[192:193], v[0:1] op_sel_hi:[1,0]
	s_nop 0
	v_pk_mul_f32 v[90:91], v[174:175], v[0:1] op_sel_hi:[1,0]
	ds_write_b128 v152, v[76:79]
	ds_write_b128 v152, v[80:83] offset:16
	ds_write_b128 v152, v[84:87] offset:256
	ds_write_b128 v152, v[88:91] offset:272
	s_and_b64 exec, exec, s[38:39]
	s_cbranch_execz .LBB0_426
	v_mov_b32_e32 v2, 0
	v_lshlrev_b32_e32 v0, 16, v133
	v_mul_f32_e32 v0, 0xbfb8aa3b, v0
	v_exp_f32_e32 v0, v0
	s_mov_b32 s27, 0xbfb8aa3b
	v_add_f32_e32 v0, 1.0, v0
	v_rcp_f32_e32 v1, v0
	v_lshlrev_b32_e32 v0, 16, v99
	v_add_f32_e32 v0, v132, v0
	v_max_f32_e32 v76, 0, v0
	v_mul_f32_e64 v0, |v0|, s27
	v_exp_f32_e32 v0, v0
	s_mov_b32 s27, 0x3f317217
	v_add_f32_e32 v0, 1.0, v0
	v_cmp_gt_f32_e32 vcc, s92, v0
	s_nop 1
	v_cndmask_b32_e64 v77, 0, 32, vcc
	v_ldexp_f32 v0, v0, v77
	v_log_f32_e32 v0, v0
	s_nop 0
	v_mul_f32_e32 v77, 0x3f317217, v0
	v_fma_f32 v77, v0, s27, -v77
	v_fmac_f32_e32 v77, 0x3377d1cf, v0
	s_mov_b32 s27, 0x7f800000
	v_fmac_f32_e32 v77, 0x3f317217, v0
	v_cmp_lt_f32_e64 s[44:45], |v0|, s27
	s_nop 1
	v_cndmask_b32_e64 v0, v0, v77, s[44:45]
	v_cndmask_b32_e32 v77, 0, v163, vcc
	v_sub_f32_e32 v0, v0, v77
	v_add_f32_e32 v0, v76, v0
	v_mul_f32_e32 v0, v0, v146
	v_mul_f32_e32 v0, 0xbfb8aa3b, v0
	v_exp_f32_e32 v0, v0
	ds_write_b128 v142, v[0:3] offset:36864

; __device__ __forceinline__ unsigned pk2(float lo, float hi) { const f32x2_t v = {lo, hi}; const bf16x2_t b = __builtin_convertvector(v, bf16x2_t); return __builtin_bit_cast(unsigned, b); }
; __device__ __forceinline__ float red8d(float x) { x += dpp_x1(x); x += dpp_x2(x); x += dpp_hm(x); return x; }
; template <int MIX>
; __device__ __forceinline__ void scan_part(const Params& p, const int layer, const int smp, const int b0, const int bstep, const int bend, const int h, const int part, char* lds, const int tid) {
;     ...
;     if (MIX == 0) {
;       if (valid) {
;         *(uint4*)(rawb + (3 + tt) * RS + 0 + sub * 8) = R0;
;         *(uint4*)(rawb + (3 + tt) * RS + 64 + sub * 8) = R1;
;         if (VN == 4) *(uint2*)(rawb + (3 + tt) * RS + 128 + sub * 4) = R2;
;         else *(unsigned*)(rawb + (3 + tt) * RS + 128 + sub * 2) = R2.x;
;       }
;     ...
;     __syncthreads();
;     if (valid) {
;       float o[VN];
; #pragma unroll
;       for (int i = 0; i < VN; ++i) o[i] = obuf[tt * CW + sub * VN + i];
;       float s1 = 0.f, s2 = 0.f;
; #pragma unroll
;       for (int i = 0; i < VN; ++i) { s1 += o[i]; s2 += o[i] * o[i]; }
;       s1 = red8d(s1); s2 = red8d(s2);
;       if (VN == 4) { uint2 o2; o2.x = pk2(o[0], o[1]); o2.y = pk2(o[2 % VN], o[3 % VN]); *(uint2*)(Ob + (size_t)(t0 + tt) * 1024 + sub * 4) = o2; }
;       else *(unsigned*)(Ob + (size_t)(t0 + tt) * 1024 + sub * 2) = pk2(o[0], o[1]);
;       if (sub == 0) *(float2*)(PS + (size_t)(t0 + tt) * 128) = make_float2(s1, s2);
.LBB0_436:
	s_waitcnt vmcnt(0) lgkmcnt(0)
	s_and_b64 vcc, exec, s[44:45]
	s_cbranch_vccnz .Ld_nonext
	s_sub_i32 s60, 0x810, s27
	s_min_u32 s60, s60, 32
	v_cmp_lt_i32_e64 s[62:63], 28, v131
	s_and_saveexec_b64 s[80:81], s[62:63]
	s_cbranch_execz .Ld_ncarry
	ds_write_b128 v139, v[240:243] offset:29024
	ds_write_b128 v139, v[244:247] offset:29152
	ds_write_b32 v150, v248 offset:29280
.Ld_ncarry:
	s_or_b64 exec, exec, s[80:81]
	v_cmp_gt_i32_e64 s[62:63], s60, v131
	s_and_saveexec_b64 s[80:81], s[62:63]
	s_cbranch_execz .Ld_nwrite
	ds_write_b128 v139, v[68:71] offset:38240
	ds_write_b128 v139, v[72:75] offset:38368
	ds_write_b32 v150, v97 offset:38496
.Ld_nwrite:
	s_or_b64 exec, exec, s[80:81]
	v_mov_b64_e32 v[240:241], v[68:69]
	v_mov_b64_e32 v[242:243], v[70:71]
	v_mov_b64_e32 v[244:245], v[72:73]
	v_mov_b64_e32 v[246:247], v[74:75]
	v_mov_b32_e32 v248, v97
	s_waitcnt lgkmcnt(0)
.Ld_nonext:
	s_barrier
	s_and_saveexec_b64 s[50:51], s[42:43]
	s_cbranch_execz .LBB0_439
	ds_read_b64 v[78:79], v153 offset:32768
	s_waitcnt lgkmcnt(0)
	v_pk_mul_f32 v[76:77], v[78:79], v[78:79]
	v_add_f32_e32 v0, 0, v78
	v_mov_b32_e32 v1, v77
	v_pk_mov_b32 v[76:77], v[78:79], v[76:77] op_sel:[1,0]
	v_cvt_pk_bf16_f32 v2, v78, v79
	v_pk_add_f32 v[0:1], v[0:1], v[76:77]
	v_add_u32_e32 v78, s23, v131
	v_ashrrev_i32_e32 v79, 31, v78
	v_mov_b32_dpp v76, v0 quad_perm:[1,0,3,2] row_mask:0xf bank_mask:0xf bound_ctrl:1
	v_mov_b32_dpp v77, v1 quad_perm:[1,0,3,2] row_mask:0xf bank_mask:0xf bound_ctrl:1
	v_pk_add_f32 v[0:1], v[0:1], v[76:77]
	v_lshlrev_b64 v[80:81], 11, v[78:79]
	v_lshl_add_u64 v[80:81], v[100:101], 0, v[80:81]
	v_mov_b32_dpp v76, v0 quad_perm:[2,3,0,1] row_mask:0xf bank_mask:0xf bound_ctrl:1
	v_mov_b32_dpp v77, v1 quad_perm:[2,3,0,1] row_mask:0xf bank_mask:0xf bound_ctrl:1
	v_pk_add_f32 v[0:1], v[0:1], v[76:77]
	global_store_dword v[80:81], v2, off
	s_nop 0
	v_mov_b32_dpp v76, v0 row_half_mirror row_mask:0xf bank_mask:0xf bound_ctrl:1
	v_mov_b32_dpp v77, v1 row_half_mirror row_mask:0xf bank_mask:0xf bound_ctrl:1
	s_and_b64 exec, exec, s[38:39]
	s_cbranch_execz .LBB0_439
	v_lshlrev_b64 v[78:79], 9, v[78:79]
	v_lshl_add_u64 v[78:79], s[48:49], 0, v[78:79]
	v_pk_add_f32 v[0:1], v[0:1], v[76:77]
	global_store_dwordx2 v[78:79], v[0:1], off
